# P7 sample-row down-projection split into 256 pieces of 4 K-tiles (one per workgroup, 16 bf16 slabs) instead of 128 pieces of 8 on half the workgroups; P8 sums 16 slabs
# baseline (speedup 1.0000x reference)
;     __host__ __device__ bool next(int i, Unit& u) const { return at((long)i * G + c, u); }
;     __host__ __device__ bool next(int i, Unit& u) const { if (i != 0 || c >= cnt) return false; u.pm = pm0 + c / nN; u.pn = c % nN; u.k0 = 0; u.nt = ntk; return true; }
;     __host__ __device__ void init(int M, int N, int K, int G_, int c_, int tailM_, int nsplit_) { so.init(M, N, K, G_, c_); tailM = tailM_; nsplit = nsplit_; npieces = tailM_ * so.nN * nsplit_; }
;     __host__ __device__ bool next(int i, Unit& u) const {
;         const long L = (long)i * so.G + so.c;
;         if (L >= npieces) return so.at(L - npieces, u);
;         const int p = (int)L, tu = p / nsplit, ks = p % nsplit, nts = so.ntk / nsplit;
;         u.pm = so.nM + tu / so.nN; u.pn = tu % so.nN; u.k0 = ks * nts; u.nt = nts; return true;
;     }
; __global__ void __launch_bounds__(512, 2) fwd_megakernel(Params P) {
;     ...
;         pg8::Gemm g{(const bf16_t*)(ws + WS_U), (const bf16_t*)(ws + WS_WDN), MT, DM, FF}; pg8::TailSplitOrder S; S.init(MP, DM, FF, G, bx, MS / 256, NSPLIT_DN);
.LBB0_1036:
	s_or_b64 exec, exec, s[0:1]
	v_mov_b32_e32 v153, v175
	s_cmpk_lt_i32 s2, 0x100
	s_waitcnt lgkmcnt(0)
	s_barrier
	s_cbranch_scc1 .LBB0_1041
	s_add_u32 s16, s2, 0xffffff80
	s_addc_u32 s17, 0, -1
	v_mov_b64_e32 v[0:1], 0x100
	v_cmp_lt_u64_e32 vcc, s[16:17], v[0:1]
	s_mov_b64 s[0:1], 0
	s_mov_b64 s[14:15], 0
	s_cbranch_vccz .LBB0_1039
	v_readlane_b32 s3, v255, 14
	s_and_b32 s3, s3, 56
	s_bfe_u32 s10, s16, 0x30003
	s_or_b32 s12, s10, s3
	s_lshr_b32 s10, s16, 6
	s_mov_b64 s[14:15], -1

;     __host__ __device__ bool next(int i, Unit& u) const {
;     ...
;         const int p = (int)L, tu = p / nsplit, ks = p % nsplit, nts = so.ntk / nsplit;
;         u.pm = so.nM + tu / so.nN; u.pn = tu % so.nN; u.k0 = ks * nts; u.nt = nts; return true;
.LBB0_1040:
	s_lshr_b32 s12, s2, 6
	s_add_i32 s12, s12, 64
	s_bfe_u32 s10, s2, 0x20004
	s_and_b32 s0, s2, 15
	s_lshl_b32 s0, s0, 2
	s_mov_b32 s57, 4
	s_branch .LBB0_1043

;     __host__ __device__ bool next(int i, Unit& u) const { return at((long)i * G + c, u); }
;     __host__ __device__ bool next(int i, Unit& u) const { if (i != 0 || c >= cnt) return false; u.pm = pm0 + c / nN; u.pn = c % nN; u.k0 = 0; u.nt = ntk; return true; }
;     ...
;     for (int i = 0; i < 2; ++i) { int R, C; stage_rc(tid * 16 + i * 8192, R, C); const int Rb = (R >> 5) * 64 + (Epi::PERM ? perm32(R & 31) : (R & 31));
;         voffA[i] = (unsigned)(R * K + C) * 2u; voffB[i] = (unsigned)(Rb * K + C) * 2u; }
;     const size_t kstep = (size_t)(BK * 2);
;     const size_t hstep = (size_t)HALF * K * 2;
;     const size_t tstep = 2 * hstep;
;     const size_t hstepB = (size_t)32 * K * 2;
;     const unsigned ldsw = (unsigned)wid * 1024u;
;     const int aoff = lds_byte(wr * 64 + fr, fq * 8), boff = lds_byte(wc * 32 + fr, fq * 8);
;     ...
;     Unit cur, nxt; int ui = 0;
;     if (!S.next(0, cur)) return;
;     f32x4 acc[2][2][4][2];
; #pragma unroll
;     for (int a = 0; a < 2; ++a)
; #pragma unroll
;         for (int b = 0; b < 2; ++b)
; #pragma unroll
;             for (int m = 0; m < 4; ++m)
; #pragma unroll
;                 for (int n = 0; n < 2; ++n) acc[a][b][m][n] = (f32x4){0.f, 0.f, 0.f, 0.f};
;     bf16x8 At[4][2], B0[2][2], B1[2][2];
;     const char* cA = (const char*)g.A + (size_t)cur.pm * tstep + (size_t)cur.k0 * (BK * 2); const char* cB = (const char*)g.Bt + (size_t)cur.pn * tstep + (size_t)cur.k0 * (BK * 2);
;     S.a_ready(cur);
;     if constexpr (SP2) {
;         PG8_STAGE(PG8_SB(0, 0), cB, voffB); PG8_STAGE(PG8_SB(0, 1), cB + hstepB, voffB); PG8_STAGEA(PG8_SA(0, 0), cA, voffA); PG8_STAGEA(PG8_SA(0, 1), cA + hstep, voffA);
;         if (wr == 1) PG8_BAR;
;         PG8_WAIT_V(2); PG8_BAR;
;         PG8_STAGE(PG8_SB(1, 0), cB + kstep, voffB); PG8_STAGEA(PG8_SA(1, 0), cA + kstep, voffA); PG8_STAGE(PG8_SB(1, 1), cB + hstepB + kstep, voffB);
;         PG8_WAIT_V(6); PG8_BAR;
;     } else {
;         PG8_STAGE(PG8_SB(0, 0), cB, voffB); PG8_STAGEA(PG8_SA(0, 0), cA, voffA); PG8_STAGE(PG8_SB(0, 1), cB + hstepB, voffB); PG8_STAGEA(PG8_SA(0, 1), cA + hstep, voffA);
;         if (wr == 1) PG8_BAR;
;         PG8_WAIT_V(4); PG8_BAR;
;         PG8_STAGE(PG8_SB(1, 0), cB + kstep, voffB); PG8_STAGEA(PG8_SA(1, 0), cA + kstep, voffA); PG8_STAGE(PG8_SB(1, 1), cB + hstepB + kstep, voffB);
;         PG8_WAIT_V(6); PG8_BAR;
;     }
.LBB0_1045:
	s_mov_b64 s[16:17], 0x80
	s_add_i32 m0, s49, 0x18000
	v_lshl_add_u64 v[6:7], v[6:7], 0, s[16:17]
	s_waitcnt vmcnt(2)
	s_barrier
	global_load_lds_dwordx4 v[6:7], off
	v_lshl_add_u64 v[2:3], v[2:3], 0, s[16:17]
	s_add_i32 m0, s49, 0x1a000
	s_add_i32 s55, s49, 0x8000
	s_add_i32 s56, s49, 0xa000
	global_load_lds_dwordx4 v[2:3], off
	v_lshl_add_u64 v[0:1], v[0:1], 0, s[16:17]
	s_mov_b32 m0, s55
	s_add_u32 s18, s36, 0x40080
	global_load_lds_dwordx4 v[0:1], off
	v_lshl_add_u64 v[0:1], v[4:5], 0, s[16:17]
	s_mov_b32 m0, s56
	s_addc_u32 s19, s37, 0
	global_load_lds_dwordx4 v[0:1], off
	s_add_i32 m0, s49, 0x1c000
	v_lshl_add_u64 v[0:1], s[18:19], 0, v[136:137]
	global_load_lds_dwordx4 v[0:1], off
	v_lshl_add_u64 v[0:1], s[18:19], 0, v[140:141]
	s_add_i32 m0, s49, 0x1e000
	v_and_b32_e32 v14, 15, v153
	global_load_lds_dwordx4 v[0:1], off
	v_or_b32_e32 v152, s72, v14
	v_lshlrev_b32_e32 v15, 6, v152
	v_and_b32_e32 v16, 48, v153
	s_movk_i32 s11, 0x3c0
	v_lshlrev_b32_e32 v17, 2, v152
	v_and_or_b32 v15, v15, s11, v16
	v_and_b32_e32 v17, 32, v17
	v_readlane_b32 s11, v255, 18
	v_lshlrev_b32_e32 v2, 2, v153
	v_lshl_or_b32 v1, v14, 6, v16
	v_bitop3_b32 v0, v15, s11, v17 bitop3:0xde
	v_and_b32_e32 v2, 32, v2
	v_readlane_b32 s11, v255, 19
	s_mov_b64 s[20:21], 0x100080
	s_waitcnt vmcnt(6)
	v_bfe_u32 v154, v153, 4, 2
	v_bitop3_b32 v163, v1, s11, v2 bitop3:0xde
	v_lshlrev_b32_e32 v1, 16, v8
	v_and_b32_e32 v1, 0xfffe0000, v1
	v_lshl_add_u32 v1, v9, 13, v1
	v_and_b32_e32 v2, 1, v8
	v_lshl_or_b32 v1, v2, 6, v1
	v_lshl_add_u32 v128, v10, 1, v1
	v_lshlrev_b32_e32 v1, 16, v11
	v_and_b32_e32 v1, 0xfffe0000, v1
	v_lshl_add_u32 v1, v12, 13, v1
	v_and_b32_e32 v2, 1, v11
	v_readlane_b32 s11, v255, 10
	v_lshl_or_b32 v1, v2, 6, v1
	s_cmpk_lt_u32 s11, 0x100
	v_lshl_add_u64 v[142:143], v[128:129], 0, s[20:21]
	v_lshl_add_u32 v128, v13, 1, v1
	s_cselect_b64 s[18:19], -1, 0
	s_addk_i32 s72, 0xc000
	v_lshl_add_u64 v[144:145], v[128:129], 0, s[20:21]
	v_mov_b32_e32 v128, v129
	v_or_b32_e32 v162, s72, v14
	v_mov_b32_e32 v130, v129
	v_mov_b32_e32 v131, v129
	v_add_u32_e32 v164, 0, v0
	v_mov_b64_e32 v[0:1], v[128:129]
	v_mov_b64_e32 v[4:5], v[128:129]
	v_mov_b64_e32 v[16:17], v[128:129]
	v_mov_b64_e32 v[20:21], v[128:129]
	v_mov_b64_e32 v[32:33], v[128:129]
	v_mov_b64_e32 v[36:37], v[128:129]
	v_mov_b64_e32 v[48:49], v[128:129]
	v_mov_b64_e32 v[52:53], v[128:129]
	v_mov_b64_e32 v[8:9], v[128:129]
	v_mov_b64_e32 v[12:13], v[128:129]
	v_mov_b64_e32 v[24:25], v[128:129]
	v_mov_b64_e32 v[28:29], v[128:129]
	v_mov_b64_e32 v[40:41], v[128:129]
	v_mov_b64_e32 v[44:45], v[128:129]
	v_mov_b64_e32 v[56:57], v[128:129]
	v_mov_b64_e32 v[60:61], v[128:129]
	v_mov_b64_e32 v[64:65], v[128:129]
	v_mov_b64_e32 v[68:69], v[128:129]
	v_mov_b64_e32 v[80:81], v[128:129]
	v_mov_b64_e32 v[84:85], v[128:129]
	v_mov_b64_e32 v[96:97], v[128:129]
	v_mov_b64_e32 v[100:101], v[128:129]
	v_mov_b64_e32 v[112:113], v[128:129]
	v_mov_b64_e32 v[116:117], v[128:129]
	v_mov_b64_e32 v[72:73], v[128:129]
	v_mov_b64_e32 v[76:77], v[128:129]
	v_mov_b64_e32 v[88:89], v[128:129]
	v_mov_b64_e32 v[92:93], v[128:129]
	v_mov_b64_e32 v[104:105], v[128:129]
	v_mov_b64_e32 v[108:109], v[128:129]
	v_mov_b64_e32 v[120:121], v[128:129]
	v_mov_b64_e32 v[124:125], v[128:129]
	v_and_b32_e32 v133, 63, v153
	v_lshlrev_b32_e32 v132, 3, v154
	s_lshl_b32 s46, s48, 6
	v_or_b32_e32 v161, 16, v162
	v_or_b32_e32 v160, 32, v162
	v_or_b32_e32 v159, 48, v162
	v_add_u32_e32 v158, 0x80, v162
	v_add_u32_e32 v157, 0x90, v162
	v_add_u32_e32 v156, 0xa0, v162
	v_add_u32_e32 v155, 0xb0, v162
	s_ashr_i32 s58, s2, 31
	v_mov_b64_e32 v[146:147], 0x100
	s_add_i32 s59, 0, 0x10000
	s_add_i32 s70, 0, 0x14000
	s_mov_b64 s[20:21], 0x100
	v_mov_b64_e32 v[148:149], 0xff
	v_mov_b64_e32 v[2:3], v[130:131]
	v_mov_b64_e32 v[6:7], v[130:131]
	v_mov_b64_e32 v[18:19], v[130:131]
	v_mov_b64_e32 v[22:23], v[130:131]
	v_mov_b64_e32 v[34:35], v[130:131]
	v_mov_b64_e32 v[38:39], v[130:131]
	v_mov_b64_e32 v[50:51], v[130:131]
	v_mov_b64_e32 v[54:55], v[130:131]
	v_mov_b64_e32 v[10:11], v[130:131]
	v_mov_b64_e32 v[14:15], v[130:131]
	v_mov_b64_e32 v[26:27], v[130:131]
	v_mov_b64_e32 v[30:31], v[130:131]
	v_mov_b64_e32 v[42:43], v[130:131]
	v_mov_b64_e32 v[46:47], v[130:131]
	v_mov_b64_e32 v[58:59], v[130:131]
	v_mov_b64_e32 v[62:63], v[130:131]
	v_mov_b64_e32 v[66:67], v[130:131]
	v_mov_b64_e32 v[70:71], v[130:131]
	v_mov_b64_e32 v[82:83], v[130:131]
	v_mov_b64_e32 v[86:87], v[130:131]
	v_mov_b64_e32 v[98:99], v[130:131]
	v_mov_b64_e32 v[102:103], v[130:131]
	v_mov_b64_e32 v[114:115], v[130:131]
	v_mov_b64_e32 v[118:119], v[130:131]
	v_mov_b64_e32 v[74:75], v[130:131]
	v_mov_b64_e32 v[78:79], v[130:131]
	v_mov_b64_e32 v[90:91], v[130:131]
	v_mov_b64_e32 v[94:95], v[130:131]
	v_mov_b64_e32 v[106:107], v[130:131]
	v_mov_b64_e32 v[110:111], v[130:131]
	v_mov_b64_e32 v[122:123], v[130:131]
	v_mov_b64_e32 v[126:127], v[130:131]
	s_mov_b32 s11, 0
	s_barrier
	s_branch .LBB0_1048

;     __host__ __device__ bool next(int i, Unit& u) const { return at((long)i * G + c, u); }
;     __host__ __device__ bool next(int i, Unit& u) const { if (i != 0 || c >= cnt) return false; u.pm = pm0 + c / nN; u.pn = c % nN; u.k0 = 0; u.nt = ntk; return true; }
;     __host__ __device__ bool next(int i, Unit& u) const {
;         const long L = (long)i * so.G + so.c;
;         if (L >= npieces) return so.at(L - npieces, u);
;         const int p = (int)L, tu = p / nsplit, ks = p % nsplit, nts = so.ntk / nsplit;
;         u.pm = so.nM + tu / so.nN; u.pn = tu % so.nN; u.k0 = ks * nts; u.nt = nts; return true;
;     }
;     ...
;         const bool has_next = S.next(ui + 1, nxt);
;         const char* nA = has_next ? (const char*)g.A + (size_t)nxt.pm * tstep + (size_t)nxt.k0 * (BK * 2) : cA; const char* nB = has_next ? (const char*)g.Bt + (size_t)nxt.pn * tstep + (size_t)nxt.k0 * (BK * 2) : cB;
.LBB0_1048:
	s_add_i32 s72, s11, 1
	s_mul_i32 s23, s72, s96
	s_mul_hi_i32 s13, s72, s96
	s_add_u32 s28, s23, s2
	s_addc_u32 s29, s13, s58
	v_cmp_lt_i64_e32 vcc, s[28:29], v[146:147]
	s_mov_b64 s[30:31], -1
	s_cbranch_vccnz .LBB0_1051
	s_add_u32 s34, s28, 0xffffff00
	s_addc_u32 s35, s29, -1
	v_cmp_gt_u64_e32 vcc, s[34:35], v[148:149]
	s_mov_b64 s[30:31], 0
	s_mov_b64 s[40:41], 0
	s_cbranch_vccnz .LBB0_1051
	s_lshl_b32 s13, s28, 3
	s_and_b32 s13, s13, 56
	s_bfe_u32 s22, s34, 0x30003
	s_or_b32 s22, s22, s13
	s_lshr_b32 s24, s34, 6
	s_mov_b32 s71, 64
	s_mov_b32 s26, 0
	s_mov_b64 s[40:41], -1
.LBB0_1051:
	s_andn2_b64 vcc, exec, s[30:31]
	s_cbranch_vccnz .LBB0_1053
	s_lshr_b32 s22, s28, 6
	s_add_i32 s22, s22, 64
	s_bfe_u32 s24, s28, 0x20004
	s_and_b32 s26, s28, 15
	s_lshl_b32 s26, s26, 2
	s_mov_b64 s[40:41], -1
	s_mov_b32 s71, 4

; DI float bflo(unsigned u) { return __uint_as_float(u << 16); }
; DI float bfhi(unsigned u) { return __uint_as_float(u & 0xffff0000u); }
; DI void final_norm(const Params& P, int G, int wave, int lane, float* dst) {
;     ...
;     for (int m = MP + gw; m < MT; m += NGW) {
;         f32x4 v[4]; float s = 0.f;
; #pragma unroll
;         for (int j = 0; j < 4; ++j) { const u32x2 hb = *(const u32x2*)(h1b + (size_t)m * DM + 4 * lane + 256 * j); v[j] = (f32x4){bflo(hb.x), bfhi(hb.x), bflo(hb.y), bfhi(hb.y)}; }
;         const bf16_t* sl = (const bf16_t*)(P.ws + WS_SLAB) + (size_t)(m - MP) * DM + 4 * lane;
; #pragma unroll
;         for (int q = 0; q < NSPLIT_DN; ++q)
; #pragma unroll
;             for (int j = 0; j < 4; ++j) { const u32x2 sb = *(const u32x2*)(sl + (size_t)q * ((size_t)MS * DM) + 256 * j); v[j] += (f32x4){bflo(sb.x), bfhi(sb.x), bflo(sb.y), bfhi(sb.y)}; }
.Lp8_row:
	s_lshl_b32 s0, s64, 11
	s_add_u32 s4, s0, 0xfc00000
	s_add_u32 s4, s68, s4
	s_addc_u32 s5, s69, 0
	s_add_u32 s6, s0, 0xba00000
	s_add_u32 s6, s68, s6
	s_addc_u32 s7, s69, 0
	s_nop 0
	global_load_dwordx2 v[16:17], v0, s[4:5]
	global_load_dwordx2 v[18:19], v0, s[4:5] offset:512
	global_load_dwordx2 v[20:21], v0, s[4:5] offset:1024
	global_load_dwordx2 v[22:23], v0, s[4:5] offset:1536
	global_load_dwordx2 v[24:25], v0, s[6:7]
	global_load_dwordx2 v[26:27], v0, s[6:7] offset:512
	global_load_dwordx2 v[28:29], v0, s[6:7] offset:1024
	global_load_dwordx2 v[30:31], v0, s[6:7] offset:1536
	s_add_u32 s6, s6, 0x200000
	s_addc_u32 s7, s7, 0
	s_nop 0
	global_load_dwordx2 v[32:33], v0, s[6:7]
	global_load_dwordx2 v[34:35], v0, s[6:7] offset:512
	global_load_dwordx2 v[36:37], v0, s[6:7] offset:1024
	global_load_dwordx2 v[38:39], v0, s[6:7] offset:1536
	s_add_u32 s6, s6, 0x200000
	s_addc_u32 s7, s7, 0
	s_nop 0
	global_load_dwordx2 v[40:41], v0, s[6:7]
	global_load_dwordx2 v[42:43], v0, s[6:7] offset:512
	global_load_dwordx2 v[44:45], v0, s[6:7] offset:1024
	global_load_dwordx2 v[46:47], v0, s[6:7] offset:1536
	s_add_u32 s6, s6, 0x200000
	s_addc_u32 s7, s7, 0
	s_nop 0
	global_load_dwordx2 v[48:49], v0, s[6:7]
	global_load_dwordx2 v[50:51], v0, s[6:7] offset:512
	global_load_dwordx2 v[52:53], v0, s[6:7] offset:1024
	global_load_dwordx2 v[54:55], v0, s[6:7] offset:1536
	s_add_u32 s6, s6, 0x200000
	s_addc_u32 s7, s7, 0
	s_nop 0
	global_load_dwordx2 v[56:57], v0, s[6:7]
	global_load_dwordx2 v[58:59], v0, s[6:7] offset:512
	global_load_dwordx2 v[60:61], v0, s[6:7] offset:1024
	global_load_dwordx2 v[62:63], v0, s[6:7] offset:1536
	s_add_u32 s6, s6, 0x200000
	s_addc_u32 s7, s7, 0
	s_nop 0
	global_load_dwordx2 v[64:65], v0, s[6:7]
	global_load_dwordx2 v[66:67], v0, s[6:7] offset:512
	global_load_dwordx2 v[68:69], v0, s[6:7] offset:1024
	global_load_dwordx2 v[70:71], v0, s[6:7] offset:1536
	s_add_u32 s6, s6, 0x200000
	s_addc_u32 s7, s7, 0
	s_nop 0
	global_load_dwordx2 v[72:73], v0, s[6:7]
	global_load_dwordx2 v[74:75], v0, s[6:7] offset:512
	global_load_dwordx2 v[76:77], v0, s[6:7] offset:1024
	global_load_dwordx2 v[78:79], v0, s[6:7] offset:1536
	s_add_u32 s6, s6, 0x200000
	s_addc_u32 s7, s7, 0
	s_nop 0
	global_load_dwordx2 v[80:81], v0, s[6:7]
	global_load_dwordx2 v[82:83], v0, s[6:7] offset:512
	global_load_dwordx2 v[84:85], v0, s[6:7] offset:1024
	global_load_dwordx2 v[86:87], v0, s[6:7] offset:1536
	s_add_u32 s6, s6, 0x200000
	s_addc_u32 s7, s7, 0
	s_nop 0
	global_load_dwordx2 v[88:89], v0, s[6:7]
	global_load_dwordx2 v[90:91], v0, s[6:7] offset:512
	global_load_dwordx2 v[92:93], v0, s[6:7] offset:1024
	global_load_dwordx2 v[94:95], v0, s[6:7] offset:1536
	s_add_u32 s6, s6, 0x200000
	s_addc_u32 s7, s7, 0
	s_nop 0
	global_load_dwordx2 v[96:97], v0, s[6:7]
	global_load_dwordx2 v[98:99], v0, s[6:7] offset:512
	global_load_dwordx2 v[100:101], v0, s[6:7] offset:1024
	global_load_dwordx2 v[102:103], v0, s[6:7] offset:1536
	s_add_u32 s6, s6, 0x200000
	s_addc_u32 s7, s7, 0
	s_nop 0
	global_load_dwordx2 v[104:105], v0, s[6:7]
	global_load_dwordx2 v[106:107], v0, s[6:7] offset:512
	global_load_dwordx2 v[108:109], v0, s[6:7] offset:1024
	global_load_dwordx2 v[110:111], v0, s[6:7] offset:1536
	s_add_u32 s6, s6, 0x200000
	s_addc_u32 s7, s7, 0
	s_nop 0
	global_load_dwordx2 v[112:113], v0, s[6:7]
	global_load_dwordx2 v[114:115], v0, s[6:7] offset:512
	global_load_dwordx2 v[116:117], v0, s[6:7] offset:1024
	global_load_dwordx2 v[118:119], v0, s[6:7] offset:1536
	s_add_u32 s6, s6, 0x200000
	s_addc_u32 s7, s7, 0
	s_nop 0
	global_load_dwordx2 v[120:121], v0, s[6:7]
	global_load_dwordx2 v[122:123], v0, s[6:7] offset:512
	global_load_dwordx2 v[124:125], v0, s[6:7] offset:1024
	global_load_dwordx2 v[126:127], v0, s[6:7] offset:1536
	s_add_u32 s6, s6, 0x200000
	s_addc_u32 s7, s7, 0
	s_nop 0
	global_load_dwordx2 v[128:129], v0, s[6:7]
	global_load_dwordx2 v[130:131], v0, s[6:7] offset:512
	global_load_dwordx2 v[132:133], v0, s[6:7] offset:1024
	global_load_dwordx2 v[134:135], v0, s[6:7] offset:1536
	s_add_u32 s6, s6, 0x200000
	s_addc_u32 s7, s7, 0
	s_nop 0
	global_load_dwordx2 v[136:137], v0, s[6:7]
	global_load_dwordx2 v[138:139], v0, s[6:7] offset:512
	global_load_dwordx2 v[140:141], v0, s[6:7] offset:1024
	global_load_dwordx2 v[142:143], v0, s[6:7] offset:1536
	s_add_u32 s6, s6, 0x200000
	s_addc_u32 s7, s7, 0
	s_nop 0
	global_load_dwordx2 v[144:145], v0, s[6:7]
	global_load_dwordx2 v[146:147], v0, s[6:7] offset:512
	global_load_dwordx2 v[148:149], v0, s[6:7] offset:1024
	global_load_dwordx2 v[150:151], v0, s[6:7] offset:1536
	s_add_i32 s0, s64, 0x4000
	s_ashr_i32 s1, s0, 31
	s_lshl_b64 s[0:1], s[0:1], 12
	s_add_u32 s8, s62, s0
	s_addc_u32 s9, s63, s1
	s_waitcnt vmcnt(0)
; DI float bflo(unsigned u) { return __uint_as_float(u << 16); }
; DI float bfhi(unsigned u) { return __uint_as_float(u & 0xffff0000u); }
; DI void final_norm(const Params& P, int G, int wave, int lane, float* dst) {
;     ...
;         for (int j = 0; j < 4; ++j) { const u32x2 hb = *(const u32x2*)(h1b + (size_t)m * DM + 4 * lane + 256 * j); v[j] = (f32x4){bflo(hb.x), bfhi(hb.x), bflo(hb.y), bfhi(hb.y)}; }
;         const bf16_t* sl = (const bf16_t*)(P.ws + WS_SLAB) + (size_t)(m - MP) * DM + 4 * lane;
; #pragma unroll
;         for (int q = 0; q < NSPLIT_DN; ++q)
; #pragma unroll
;             for (int j = 0; j < 4; ++j) { const u32x2 sb = *(const u32x2*)(sl + (size_t)q * ((size_t)MS * DM) + 256 * j); v[j] += (f32x4){bflo(sb.x), bfhi(sb.x), bflo(sb.y), bfhi(sb.y)}; }
	v_lshlrev_b32_e32 v200, 16, v16
	v_and_b32_e32 v201, 0xffff0000, v16
	v_lshlrev_b32_e32 v202, 16, v17
	v_and_b32_e32 v203, 0xffff0000, v17
	v_lshlrev_b32_e32 v204, 16, v18
	v_and_b32_e32 v205, 0xffff0000, v18
	v_lshlrev_b32_e32 v206, 16, v19
	v_and_b32_e32 v207, 0xffff0000, v19
	v_lshlrev_b32_e32 v208, 16, v20
	v_and_b32_e32 v209, 0xffff0000, v20
	v_lshlrev_b32_e32 v210, 16, v21
	v_and_b32_e32 v211, 0xffff0000, v21
	v_lshlrev_b32_e32 v212, 16, v22
	v_and_b32_e32 v213, 0xffff0000, v22
	v_lshlrev_b32_e32 v214, 16, v23
	v_and_b32_e32 v215, 0xffff0000, v23
	v_lshlrev_b32_e32 v180, 16, v24
	v_and_b32_e32 v181, 0xffff0000, v24
	v_pk_add_f32 v[200:201], v[200:201], v[180:181]
	v_lshlrev_b32_e32 v180, 16, v25
	v_and_b32_e32 v181, 0xffff0000, v25
	v_pk_add_f32 v[202:203], v[202:203], v[180:181]
	v_lshlrev_b32_e32 v180, 16, v26
	v_and_b32_e32 v181, 0xffff0000, v26
	v_pk_add_f32 v[204:205], v[204:205], v[180:181]
	v_lshlrev_b32_e32 v180, 16, v27
	v_and_b32_e32 v181, 0xffff0000, v27
	v_pk_add_f32 v[206:207], v[206:207], v[180:181]
	v_lshlrev_b32_e32 v180, 16, v28
	v_and_b32_e32 v181, 0xffff0000, v28
	v_pk_add_f32 v[208:209], v[208:209], v[180:181]
	v_lshlrev_b32_e32 v180, 16, v29
	v_and_b32_e32 v181, 0xffff0000, v29
	v_pk_add_f32 v[210:211], v[210:211], v[180:181]
	v_lshlrev_b32_e32 v180, 16, v30
	v_and_b32_e32 v181, 0xffff0000, v30
	v_pk_add_f32 v[212:213], v[212:213], v[180:181]
	v_lshlrev_b32_e32 v180, 16, v31
	v_and_b32_e32 v181, 0xffff0000, v31
	v_pk_add_f32 v[214:215], v[214:215], v[180:181]
	v_lshlrev_b32_e32 v180, 16, v32
	v_and_b32_e32 v181, 0xffff0000, v32
	v_pk_add_f32 v[200:201], v[200:201], v[180:181]
	v_lshlrev_b32_e32 v180, 16, v33
	v_and_b32_e32 v181, 0xffff0000, v33
	v_pk_add_f32 v[202:203], v[202:203], v[180:181]
	v_lshlrev_b32_e32 v180, 16, v34
	v_and_b32_e32 v181, 0xffff0000, v34
	v_pk_add_f32 v[204:205], v[204:205], v[180:181]
	v_lshlrev_b32_e32 v180, 16, v35
	v_and_b32_e32 v181, 0xffff0000, v35
	v_pk_add_f32 v[206:207], v[206:207], v[180:181]
	v_lshlrev_b32_e32 v180, 16, v36
	v_and_b32_e32 v181, 0xffff0000, v36
	v_pk_add_f32 v[208:209], v[208:209], v[180:181]
	v_lshlrev_b32_e32 v180, 16, v37
	v_and_b32_e32 v181, 0xffff0000, v37
	v_pk_add_f32 v[210:211], v[210:211], v[180:181]
	v_lshlrev_b32_e32 v180, 16, v38
	v_and_b32_e32 v181, 0xffff0000, v38
	v_pk_add_f32 v[212:213], v[212:213], v[180:181]
	v_lshlrev_b32_e32 v180, 16, v39
	v_and_b32_e32 v181, 0xffff0000, v39
	v_pk_add_f32 v[214:215], v[214:215], v[180:181]
	v_lshlrev_b32_e32 v180, 16, v40
	v_and_b32_e32 v181, 0xffff0000, v40
	v_pk_add_f32 v[200:201], v[200:201], v[180:181]
	v_lshlrev_b32_e32 v180, 16, v41
	v_and_b32_e32 v181, 0xffff0000, v41
	v_pk_add_f32 v[202:203], v[202:203], v[180:181]
	v_lshlrev_b32_e32 v180, 16, v42
	v_and_b32_e32 v181, 0xffff0000, v42
	v_pk_add_f32 v[204:205], v[204:205], v[180:181]
	v_lshlrev_b32_e32 v180, 16, v43
	v_and_b32_e32 v181, 0xffff0000, v43
	v_pk_add_f32 v[206:207], v[206:207], v[180:181]
	v_lshlrev_b32_e32 v180, 16, v44
	v_and_b32_e32 v181, 0xffff0000, v44
	v_pk_add_f32 v[208:209], v[208:209], v[180:181]
	v_lshlrev_b32_e32 v180, 16, v45
	v_and_b32_e32 v181, 0xffff0000, v45
	v_pk_add_f32 v[210:211], v[210:211], v[180:181]
	v_lshlrev_b32_e32 v180, 16, v46
	v_and_b32_e32 v181, 0xffff0000, v46
	v_pk_add_f32 v[212:213], v[212:213], v[180:181]
	v_lshlrev_b32_e32 v180, 16, v47
	v_and_b32_e32 v181, 0xffff0000, v47
	v_pk_add_f32 v[214:215], v[214:215], v[180:181]
	v_lshlrev_b32_e32 v180, 16, v48
	v_and_b32_e32 v181, 0xffff0000, v48
	v_pk_add_f32 v[200:201], v[200:201], v[180:181]
	v_lshlrev_b32_e32 v180, 16, v49
	v_and_b32_e32 v181, 0xffff0000, v49
	v_pk_add_f32 v[202:203], v[202:203], v[180:181]
	v_lshlrev_b32_e32 v180, 16, v50
	v_and_b32_e32 v181, 0xffff0000, v50
	v_pk_add_f32 v[204:205], v[204:205], v[180:181]
	v_lshlrev_b32_e32 v180, 16, v51
	v_and_b32_e32 v181, 0xffff0000, v51
	v_pk_add_f32 v[206:207], v[206:207], v[180:181]
	v_lshlrev_b32_e32 v180, 16, v52
	v_and_b32_e32 v181, 0xffff0000, v52
	v_pk_add_f32 v[208:209], v[208:209], v[180:181]
	v_lshlrev_b32_e32 v180, 16, v53
	v_and_b32_e32 v181, 0xffff0000, v53
	v_pk_add_f32 v[210:211], v[210:211], v[180:181]
	v_lshlrev_b32_e32 v180, 16, v54
	v_and_b32_e32 v181, 0xffff0000, v54
	v_pk_add_f32 v[212:213], v[212:213], v[180:181]
	v_lshlrev_b32_e32 v180, 16, v55
	v_and_b32_e32 v181, 0xffff0000, v55
	v_pk_add_f32 v[214:215], v[214:215], v[180:181]
	v_lshlrev_b32_e32 v180, 16, v56
	v_and_b32_e32 v181, 0xffff0000, v56
	v_pk_add_f32 v[200:201], v[200:201], v[180:181]
	v_lshlrev_b32_e32 v180, 16, v57
	v_and_b32_e32 v181, 0xffff0000, v57
	v_pk_add_f32 v[202:203], v[202:203], v[180:181]
	v_lshlrev_b32_e32 v180, 16, v58
	v_and_b32_e32 v181, 0xffff0000, v58
	v_pk_add_f32 v[204:205], v[204:205], v[180:181]
	v_lshlrev_b32_e32 v180, 16, v59
	v_and_b32_e32 v181, 0xffff0000, v59
	v_pk_add_f32 v[206:207], v[206:207], v[180:181]
	v_lshlrev_b32_e32 v180, 16, v60
	v_and_b32_e32 v181, 0xffff0000, v60
	v_pk_add_f32 v[208:209], v[208:209], v[180:181]
	v_lshlrev_b32_e32 v180, 16, v61
	v_and_b32_e32 v181, 0xffff0000, v61
	v_pk_add_f32 v[210:211], v[210:211], v[180:181]
	v_lshlrev_b32_e32 v180, 16, v62
	v_and_b32_e32 v181, 0xffff0000, v62
	v_pk_add_f32 v[212:213], v[212:213], v[180:181]
	v_lshlrev_b32_e32 v180, 16, v63
	v_and_b32_e32 v181, 0xffff0000, v63
	v_pk_add_f32 v[214:215], v[214:215], v[180:181]
	v_lshlrev_b32_e32 v180, 16, v64
	v_and_b32_e32 v181, 0xffff0000, v64
	v_pk_add_f32 v[200:201], v[200:201], v[180:181]
	v_lshlrev_b32_e32 v180, 16, v65
	v_and_b32_e32 v181, 0xffff0000, v65
	v_pk_add_f32 v[202:203], v[202:203], v[180:181]
	v_lshlrev_b32_e32 v180, 16, v66
	v_and_b32_e32 v181, 0xffff0000, v66
; DI float bflo(unsigned u) { return __uint_as_float(u << 16); }
; DI float bfhi(unsigned u) { return __uint_as_float(u & 0xffff0000u); }
; DI void final_norm(const Params& P, int G, int wave, int lane, float* dst) {
;     ...
;         for (int q = 0; q < NSPLIT_DN; ++q)
; #pragma unroll
;             for (int j = 0; j < 4; ++j) { const u32x2 sb = *(const u32x2*)(sl + (size_t)q * ((size_t)MS * DM) + 256 * j); v[j] += (f32x4){bflo(sb.x), bfhi(sb.x), bflo(sb.y), bfhi(sb.y)}; }
	v_pk_add_f32 v[204:205], v[204:205], v[180:181]
	v_lshlrev_b32_e32 v180, 16, v67
	v_and_b32_e32 v181, 0xffff0000, v67
	v_pk_add_f32 v[206:207], v[206:207], v[180:181]
	v_lshlrev_b32_e32 v180, 16, v68
	v_and_b32_e32 v181, 0xffff0000, v68
	v_pk_add_f32 v[208:209], v[208:209], v[180:181]
	v_lshlrev_b32_e32 v180, 16, v69
	v_and_b32_e32 v181, 0xffff0000, v69
	v_pk_add_f32 v[210:211], v[210:211], v[180:181]
	v_lshlrev_b32_e32 v180, 16, v70
	v_and_b32_e32 v181, 0xffff0000, v70
	v_pk_add_f32 v[212:213], v[212:213], v[180:181]
	v_lshlrev_b32_e32 v180, 16, v71
	v_and_b32_e32 v181, 0xffff0000, v71
	v_pk_add_f32 v[214:215], v[214:215], v[180:181]
	v_lshlrev_b32_e32 v180, 16, v72
	v_and_b32_e32 v181, 0xffff0000, v72
	v_pk_add_f32 v[200:201], v[200:201], v[180:181]
	v_lshlrev_b32_e32 v180, 16, v73
	v_and_b32_e32 v181, 0xffff0000, v73
	v_pk_add_f32 v[202:203], v[202:203], v[180:181]
	v_lshlrev_b32_e32 v180, 16, v74
	v_and_b32_e32 v181, 0xffff0000, v74
	v_pk_add_f32 v[204:205], v[204:205], v[180:181]
	v_lshlrev_b32_e32 v180, 16, v75
	v_and_b32_e32 v181, 0xffff0000, v75
	v_pk_add_f32 v[206:207], v[206:207], v[180:181]
	v_lshlrev_b32_e32 v180, 16, v76
	v_and_b32_e32 v181, 0xffff0000, v76
	v_pk_add_f32 v[208:209], v[208:209], v[180:181]
	v_lshlrev_b32_e32 v180, 16, v77
	v_and_b32_e32 v181, 0xffff0000, v77
	v_pk_add_f32 v[210:211], v[210:211], v[180:181]
	v_lshlrev_b32_e32 v180, 16, v78
	v_and_b32_e32 v181, 0xffff0000, v78
	v_pk_add_f32 v[212:213], v[212:213], v[180:181]
	v_lshlrev_b32_e32 v180, 16, v79
	v_and_b32_e32 v181, 0xffff0000, v79
	v_pk_add_f32 v[214:215], v[214:215], v[180:181]
	v_lshlrev_b32_e32 v180, 16, v80
	v_and_b32_e32 v181, 0xffff0000, v80
	v_pk_add_f32 v[200:201], v[200:201], v[180:181]
	v_lshlrev_b32_e32 v180, 16, v81
	v_and_b32_e32 v181, 0xffff0000, v81
	v_pk_add_f32 v[202:203], v[202:203], v[180:181]
	v_lshlrev_b32_e32 v180, 16, v82
	v_and_b32_e32 v181, 0xffff0000, v82
	v_pk_add_f32 v[204:205], v[204:205], v[180:181]
	v_lshlrev_b32_e32 v180, 16, v83
	v_and_b32_e32 v181, 0xffff0000, v83
	v_pk_add_f32 v[206:207], v[206:207], v[180:181]
	v_lshlrev_b32_e32 v180, 16, v84
	v_and_b32_e32 v181, 0xffff0000, v84
	v_pk_add_f32 v[208:209], v[208:209], v[180:181]
	v_lshlrev_b32_e32 v180, 16, v85
	v_and_b32_e32 v181, 0xffff0000, v85
	v_pk_add_f32 v[210:211], v[210:211], v[180:181]
	v_lshlrev_b32_e32 v180, 16, v86
	v_and_b32_e32 v181, 0xffff0000, v86
	v_pk_add_f32 v[212:213], v[212:213], v[180:181]
	v_lshlrev_b32_e32 v180, 16, v87
	v_and_b32_e32 v181, 0xffff0000, v87
	v_pk_add_f32 v[214:215], v[214:215], v[180:181]
	v_lshlrev_b32_e32 v180, 16, v88
	v_and_b32_e32 v181, 0xffff0000, v88
	v_pk_add_f32 v[200:201], v[200:201], v[180:181]
	v_lshlrev_b32_e32 v180, 16, v89
	v_and_b32_e32 v181, 0xffff0000, v89
	v_pk_add_f32 v[202:203], v[202:203], v[180:181]
	v_lshlrev_b32_e32 v180, 16, v90
	v_and_b32_e32 v181, 0xffff0000, v90
	v_pk_add_f32 v[204:205], v[204:205], v[180:181]
	v_lshlrev_b32_e32 v180, 16, v91
	v_and_b32_e32 v181, 0xffff0000, v91
	v_pk_add_f32 v[206:207], v[206:207], v[180:181]
	v_lshlrev_b32_e32 v180, 16, v92
	v_and_b32_e32 v181, 0xffff0000, v92
	v_pk_add_f32 v[208:209], v[208:209], v[180:181]
	v_lshlrev_b32_e32 v180, 16, v93
	v_and_b32_e32 v181, 0xffff0000, v93
	v_pk_add_f32 v[210:211], v[210:211], v[180:181]
	v_lshlrev_b32_e32 v180, 16, v94
	v_and_b32_e32 v181, 0xffff0000, v94
	v_pk_add_f32 v[212:213], v[212:213], v[180:181]
	v_lshlrev_b32_e32 v180, 16, v95
	v_and_b32_e32 v181, 0xffff0000, v95
	v_pk_add_f32 v[214:215], v[214:215], v[180:181]
	v_lshlrev_b32_e32 v180, 16, v96
	v_and_b32_e32 v181, 0xffff0000, v96
	v_pk_add_f32 v[200:201], v[200:201], v[180:181]
	v_lshlrev_b32_e32 v180, 16, v97
	v_and_b32_e32 v181, 0xffff0000, v97
	v_pk_add_f32 v[202:203], v[202:203], v[180:181]
	v_lshlrev_b32_e32 v180, 16, v98
	v_and_b32_e32 v181, 0xffff0000, v98
	v_pk_add_f32 v[204:205], v[204:205], v[180:181]
	v_lshlrev_b32_e32 v180, 16, v99
	v_and_b32_e32 v181, 0xffff0000, v99
	v_pk_add_f32 v[206:207], v[206:207], v[180:181]
	v_lshlrev_b32_e32 v180, 16, v100
	v_and_b32_e32 v181, 0xffff0000, v100
	v_pk_add_f32 v[208:209], v[208:209], v[180:181]
	v_lshlrev_b32_e32 v180, 16, v101
	v_and_b32_e32 v181, 0xffff0000, v101
	v_pk_add_f32 v[210:211], v[210:211], v[180:181]
	v_lshlrev_b32_e32 v180, 16, v102
	v_and_b32_e32 v181, 0xffff0000, v102
	v_pk_add_f32 v[212:213], v[212:213], v[180:181]
	v_lshlrev_b32_e32 v180, 16, v103
	v_and_b32_e32 v181, 0xffff0000, v103
	v_pk_add_f32 v[214:215], v[214:215], v[180:181]
	v_lshlrev_b32_e32 v180, 16, v104
	v_and_b32_e32 v181, 0xffff0000, v104
	v_pk_add_f32 v[200:201], v[200:201], v[180:181]
	v_lshlrev_b32_e32 v180, 16, v105
	v_and_b32_e32 v181, 0xffff0000, v105
	v_pk_add_f32 v[202:203], v[202:203], v[180:181]
	v_lshlrev_b32_e32 v180, 16, v106
	v_and_b32_e32 v181, 0xffff0000, v106
	v_pk_add_f32 v[204:205], v[204:205], v[180:181]
	v_lshlrev_b32_e32 v180, 16, v107
	v_and_b32_e32 v181, 0xffff0000, v107
	v_pk_add_f32 v[206:207], v[206:207], v[180:181]
	v_lshlrev_b32_e32 v180, 16, v108
	v_and_b32_e32 v181, 0xffff0000, v108
	v_pk_add_f32 v[208:209], v[208:209], v[180:181]
	v_lshlrev_b32_e32 v180, 16, v109
	v_and_b32_e32 v181, 0xffff0000, v109
	v_pk_add_f32 v[210:211], v[210:211], v[180:181]
	v_lshlrev_b32_e32 v180, 16, v110
	v_and_b32_e32 v181, 0xffff0000, v110
	v_pk_add_f32 v[212:213], v[212:213], v[180:181]
	v_lshlrev_b32_e32 v180, 16, v111
	v_and_b32_e32 v181, 0xffff0000, v111
	v_pk_add_f32 v[214:215], v[214:215], v[180:181]
	v_lshlrev_b32_e32 v180, 16, v112
	v_and_b32_e32 v181, 0xffff0000, v112
	v_pk_add_f32 v[200:201], v[200:201], v[180:181]
	v_lshlrev_b32_e32 v180, 16, v113
	v_and_b32_e32 v181, 0xffff0000, v113
; DI float bflo(unsigned u) { return __uint_as_float(u << 16); }
; DI float bfhi(unsigned u) { return __uint_as_float(u & 0xffff0000u); }
; DI void final_norm(const Params& P, int G, int wave, int lane, float* dst) {
;     ...
;         for (int q = 0; q < NSPLIT_DN; ++q)
; #pragma unroll
;             for (int j = 0; j < 4; ++j) { const u32x2 sb = *(const u32x2*)(sl + (size_t)q * ((size_t)MS * DM) + 256 * j); v[j] += (f32x4){bflo(sb.x), bfhi(sb.x), bflo(sb.y), bfhi(sb.y)}; }
; #pragma unroll
;         for (int j = 0; j < 4; ++j) s += (v[j][0] * v[j][0] + v[j][1] * v[j][1]) + (v[j][2] * v[j][2] + v[j][3] * v[j][3]);
;         const float rs = rsqrtf(wave_sum(s) * (1.0f / DM) + EPS);
	v_pk_add_f32 v[202:203], v[202:203], v[180:181]
	v_lshlrev_b32_e32 v180, 16, v114
	v_and_b32_e32 v181, 0xffff0000, v114
	v_pk_add_f32 v[204:205], v[204:205], v[180:181]
	v_lshlrev_b32_e32 v180, 16, v115
	v_and_b32_e32 v181, 0xffff0000, v115
	v_pk_add_f32 v[206:207], v[206:207], v[180:181]
	v_lshlrev_b32_e32 v180, 16, v116
	v_and_b32_e32 v181, 0xffff0000, v116
	v_pk_add_f32 v[208:209], v[208:209], v[180:181]
	v_lshlrev_b32_e32 v180, 16, v117
	v_and_b32_e32 v181, 0xffff0000, v117
	v_pk_add_f32 v[210:211], v[210:211], v[180:181]
	v_lshlrev_b32_e32 v180, 16, v118
	v_and_b32_e32 v181, 0xffff0000, v118
	v_pk_add_f32 v[212:213], v[212:213], v[180:181]
	v_lshlrev_b32_e32 v180, 16, v119
	v_and_b32_e32 v181, 0xffff0000, v119
	v_pk_add_f32 v[214:215], v[214:215], v[180:181]
	v_lshlrev_b32_e32 v180, 16, v120
	v_and_b32_e32 v181, 0xffff0000, v120
	v_pk_add_f32 v[200:201], v[200:201], v[180:181]
	v_lshlrev_b32_e32 v180, 16, v121
	v_and_b32_e32 v181, 0xffff0000, v121
	v_pk_add_f32 v[202:203], v[202:203], v[180:181]
	v_lshlrev_b32_e32 v180, 16, v122
	v_and_b32_e32 v181, 0xffff0000, v122
	v_pk_add_f32 v[204:205], v[204:205], v[180:181]
	v_lshlrev_b32_e32 v180, 16, v123
	v_and_b32_e32 v181, 0xffff0000, v123
	v_pk_add_f32 v[206:207], v[206:207], v[180:181]
	v_lshlrev_b32_e32 v180, 16, v124
	v_and_b32_e32 v181, 0xffff0000, v124
	v_pk_add_f32 v[208:209], v[208:209], v[180:181]
	v_lshlrev_b32_e32 v180, 16, v125
	v_and_b32_e32 v181, 0xffff0000, v125
	v_pk_add_f32 v[210:211], v[210:211], v[180:181]
	v_lshlrev_b32_e32 v180, 16, v126
	v_and_b32_e32 v181, 0xffff0000, v126
	v_pk_add_f32 v[212:213], v[212:213], v[180:181]
	v_lshlrev_b32_e32 v180, 16, v127
	v_and_b32_e32 v181, 0xffff0000, v127
	v_pk_add_f32 v[214:215], v[214:215], v[180:181]
	v_lshlrev_b32_e32 v180, 16, v128
	v_and_b32_e32 v181, 0xffff0000, v128
	v_pk_add_f32 v[200:201], v[200:201], v[180:181]
	v_lshlrev_b32_e32 v180, 16, v129
	v_and_b32_e32 v181, 0xffff0000, v129
	v_pk_add_f32 v[202:203], v[202:203], v[180:181]
	v_lshlrev_b32_e32 v180, 16, v130
	v_and_b32_e32 v181, 0xffff0000, v130
	v_pk_add_f32 v[204:205], v[204:205], v[180:181]
	v_lshlrev_b32_e32 v180, 16, v131
	v_and_b32_e32 v181, 0xffff0000, v131
	v_pk_add_f32 v[206:207], v[206:207], v[180:181]
	v_lshlrev_b32_e32 v180, 16, v132
	v_and_b32_e32 v181, 0xffff0000, v132
	v_pk_add_f32 v[208:209], v[208:209], v[180:181]
	v_lshlrev_b32_e32 v180, 16, v133
	v_and_b32_e32 v181, 0xffff0000, v133
	v_pk_add_f32 v[210:211], v[210:211], v[180:181]
	v_lshlrev_b32_e32 v180, 16, v134
	v_and_b32_e32 v181, 0xffff0000, v134
	v_pk_add_f32 v[212:213], v[212:213], v[180:181]
	v_lshlrev_b32_e32 v180, 16, v135
	v_and_b32_e32 v181, 0xffff0000, v135
	v_pk_add_f32 v[214:215], v[214:215], v[180:181]
	v_lshlrev_b32_e32 v180, 16, v136
	v_and_b32_e32 v181, 0xffff0000, v136
	v_pk_add_f32 v[200:201], v[200:201], v[180:181]
	v_lshlrev_b32_e32 v180, 16, v137
	v_and_b32_e32 v181, 0xffff0000, v137
	v_pk_add_f32 v[202:203], v[202:203], v[180:181]
	v_lshlrev_b32_e32 v180, 16, v138
	v_and_b32_e32 v181, 0xffff0000, v138
	v_pk_add_f32 v[204:205], v[204:205], v[180:181]
	v_lshlrev_b32_e32 v180, 16, v139
	v_and_b32_e32 v181, 0xffff0000, v139
	v_pk_add_f32 v[206:207], v[206:207], v[180:181]
	v_lshlrev_b32_e32 v180, 16, v140
	v_and_b32_e32 v181, 0xffff0000, v140
	v_pk_add_f32 v[208:209], v[208:209], v[180:181]
	v_lshlrev_b32_e32 v180, 16, v141
	v_and_b32_e32 v181, 0xffff0000, v141
	v_pk_add_f32 v[210:211], v[210:211], v[180:181]
	v_lshlrev_b32_e32 v180, 16, v142
	v_and_b32_e32 v181, 0xffff0000, v142
	v_pk_add_f32 v[212:213], v[212:213], v[180:181]
	v_lshlrev_b32_e32 v180, 16, v143
	v_and_b32_e32 v181, 0xffff0000, v143
	v_pk_add_f32 v[214:215], v[214:215], v[180:181]
	v_lshlrev_b32_e32 v180, 16, v144
	v_and_b32_e32 v181, 0xffff0000, v144
	v_pk_add_f32 v[200:201], v[200:201], v[180:181]
	v_lshlrev_b32_e32 v180, 16, v145
	v_and_b32_e32 v181, 0xffff0000, v145
	v_pk_add_f32 v[202:203], v[202:203], v[180:181]
	v_lshlrev_b32_e32 v180, 16, v146
	v_and_b32_e32 v181, 0xffff0000, v146
	v_pk_add_f32 v[204:205], v[204:205], v[180:181]
	v_lshlrev_b32_e32 v180, 16, v147
	v_and_b32_e32 v181, 0xffff0000, v147
	v_pk_add_f32 v[206:207], v[206:207], v[180:181]
	v_lshlrev_b32_e32 v180, 16, v148
	v_and_b32_e32 v181, 0xffff0000, v148
	v_pk_add_f32 v[208:209], v[208:209], v[180:181]
	v_lshlrev_b32_e32 v180, 16, v149
	v_and_b32_e32 v181, 0xffff0000, v149
	v_pk_add_f32 v[210:211], v[210:211], v[180:181]
	v_lshlrev_b32_e32 v180, 16, v150
	v_and_b32_e32 v181, 0xffff0000, v150
	v_pk_add_f32 v[212:213], v[212:213], v[180:181]
	v_lshlrev_b32_e32 v180, 16, v151
	v_and_b32_e32 v181, 0xffff0000, v151
	v_pk_add_f32 v[214:215], v[214:215], v[180:181]
	v_mov_b32_e32 v182, 0
	v_mul_f32_e32 v180, v200, v200
	v_fmac_f32_e32 v180, v201, v201
	v_mul_f32_e32 v181, v202, v202
	v_fmac_f32_e32 v181, v203, v203
	v_add_f32_e32 v180, v180, v181
	v_add_f32_e32 v182, v182, v180
	v_mul_f32_e32 v180, v204, v204
	v_fmac_f32_e32 v180, v205, v205
	v_mul_f32_e32 v181, v206, v206
	v_fmac_f32_e32 v181, v207, v207
	v_add_f32_e32 v180, v180, v181
	v_add_f32_e32 v182, v182, v180
	v_mul_f32_e32 v180, v208, v208
	v_fmac_f32_e32 v180, v209, v209
	v_mul_f32_e32 v181, v210, v210
	v_fmac_f32_e32 v181, v211, v211
	v_add_f32_e32 v180, v180, v181
	v_add_f32_e32 v182, v182, v180
	v_mul_f32_e32 v180, v212, v212
	v_fmac_f32_e32 v180, v213, v213
	v_mul_f32_e32 v181, v214, v214
	v_fmac_f32_e32 v181, v215, v215
	v_add_f32_e32 v180, v180, v181
	v_add_f32_e32 v182, v182, v180
	v_xor_b32_e32 v183, 4, v3
	ds_bpermute_b32 v184, v183, v182
	s_waitcnt lgkmcnt(0)
; DI void final_norm(const Params& P, int G, int wave, int lane, float* dst) {
;     ...
;         const float rs = rsqrtf(wave_sum(s) * (1.0f / DM) + EPS);
; #pragma unroll
;         for (int j = 0; j < 4; ++j) *(f32x4*)(dst + (size_t)m * DM + 4 * lane + 256 * j) = v[j] * rs * *(const f32x4*)(P.norm_f + 4 * lane + 256 * j);
;     }
	v_add_f32_e32 v182, v182, v184
	v_xor_b32_e32 v183, 8, v3
	ds_bpermute_b32 v184, v183, v182
	s_waitcnt lgkmcnt(0)
	v_add_f32_e32 v182, v182, v184
	v_xor_b32_e32 v183, 16, v3
	ds_bpermute_b32 v184, v183, v182
	s_waitcnt lgkmcnt(0)
	v_add_f32_e32 v182, v182, v184
	v_xor_b32_e32 v183, 32, v3
	ds_bpermute_b32 v184, v183, v182
	s_waitcnt lgkmcnt(0)
	v_add_f32_e32 v182, v182, v184
	v_xor_b32_e32 v183, 64, v3
	ds_bpermute_b32 v184, v183, v182
	s_waitcnt lgkmcnt(0)
	v_add_f32_e32 v182, v182, v184
	v_xor_b32_e32 v183, 128, v3
	ds_bpermute_b32 v184, v183, v182
	s_waitcnt lgkmcnt(0)
	v_add_f32_e32 v182, v182, v184
	v_mov_b32_e32 v185, 0x358637bd
	v_fmamk_f32 v182, v182, 0x3a800000, v185
	s_mov_b32 s0, 0x800000
	v_mul_f32_e32 v184, 0x4b800000, v182
	v_cmp_gt_f32_e32 vcc, s0, v182
	s_nop 1
	v_cndmask_b32_e32 v182, v182, v184, vcc
	v_rsq_f32_e32 v182, v182
	s_nop 0
	v_mul_f32_e32 v184, 0x45800000, v182
	v_cndmask_b32_e32 v186, v182, v184, vcc
	v_pk_mul_f32 v[200:201], v[200:201], v[186:187] op_sel_hi:[1,0]
	v_pk_mul_f32 v[202:203], v[202:203], v[186:187] op_sel_hi:[1,0]
	v_pk_mul_f32 v[200:201], v[160:161], v[200:201]
	v_pk_mul_f32 v[202:203], v[162:163], v[202:203]
	global_store_dwordx4 v1, v[200:203], s[8:9]
	v_pk_mul_f32 v[204:205], v[204:205], v[186:187] op_sel_hi:[1,0]
	v_pk_mul_f32 v[206:207], v[206:207], v[186:187] op_sel_hi:[1,0]
	v_pk_mul_f32 v[204:205], v[164:165], v[204:205]
	v_pk_mul_f32 v[206:207], v[166:167], v[206:207]
	global_store_dwordx4 v1, v[204:207], s[8:9] offset:1024
	v_pk_mul_f32 v[208:209], v[208:209], v[186:187] op_sel_hi:[1,0]
	v_pk_mul_f32 v[210:211], v[210:211], v[186:187] op_sel_hi:[1,0]
	v_pk_mul_f32 v[208:209], v[168:169], v[208:209]
	v_pk_mul_f32 v[210:211], v[170:171], v[210:211]
	global_store_dwordx4 v1, v[208:211], s[8:9] offset:2048
	v_pk_mul_f32 v[212:213], v[212:213], v[186:187] op_sel_hi:[1,0]
	v_pk_mul_f32 v[214:215], v[214:215], v[186:187] op_sel_hi:[1,0]
	v_pk_mul_f32 v[212:213], v[172:173], v[212:213]
	v_pk_mul_f32 v[214:215], v[174:175], v[214:215]
	global_store_dwordx4 v1, v[212:215], s[8:9] offset:3072
	s_add_i32 s64, s64, s66
	s_add_i32 s0, s64, 0x4000
	s_cmpk_lt_i32 s0, 0x4400
	s_cbranch_scc1 .Lp8_row
